# first grid barrier: the 16 census counter loads issued together with one wait instead of 15 serialized round trips
# speedup vs baseline: 1.0127x; 1.0020x over previous
; __device__ __forceinline__ unsigned xb_ld(unsigned* p)              { return __hip_atomic_load(p, __ATOMIC_RELAXED, __HIP_MEMORY_SCOPE_AGENT); }
; __device__ __forceinline__ void xcd_barrier_complete(unsigned* bar, unsigned x, unsigned& nloc, unsigned& nx) {
;     ...
;     for (;;) {
;         sum = 0u; cnt = 0u; mine = 0u;
; #pragma unroll
;         for (unsigned j = 0; j < 16; ++j) { const unsigned c = xb_ld(&bar[XB_XCNT(j)]); sum += c; cnt += (c > 0u) ? 1u : 0u; mine = (j == x) ? c : mine; }
;         if (sum == G) break;
;         __builtin_amdgcn_s_sleep(1);
;         if ((++sp & 255u) == 0u) { if (xb_ld(&bar[XB_TMO])) break; if (sp > XB_SPIN_CAP) { atomicAdd(&bar[XB_TMO], 1u); break; } }
;     }
.LBB0_129:
	v_readlane_b32 s4, v252, 20
	v_readlane_b32 s5, v252, 21
	v_readlane_b32 s7, v252, 17
	s_mov_b64 s[22:23], -1
	s_nop 2
	global_load_dword v1, v0, s[4:5] sc1
	v_readlane_b32 s4, v252, 22
	v_readlane_b32 s5, v252, 23
	s_waitcnt lgkmcnt(0)
	s_nop 3
	global_load_dword v2, v0, s[4:5] sc1
	v_readlane_b32 s4, v252, 24
	v_readlane_b32 s5, v252, 25
	s_nop 4
	global_load_dword v3, v0, s[4:5] sc1
	v_readlane_b32 s4, v252, 26
	v_readlane_b32 s5, v252, 27
	s_nop 4
	global_load_dword v4, v0, s[4:5] sc1
	v_readlane_b32 s4, v252, 28
	v_readlane_b32 s5, v252, 29
	s_nop 4
	global_load_dword v5, v0, s[4:5] sc1
	v_readlane_b32 s4, v252, 30
	v_readlane_b32 s5, v252, 31
	s_nop 4
	global_load_dword v6, v0, s[4:5] sc1
	v_readlane_b32 s4, v252, 32
	v_readlane_b32 s5, v252, 33
	s_nop 4
	global_load_dword v7, v0, s[4:5] sc1
	v_readlane_b32 s4, v252, 34
	v_readlane_b32 s5, v252, 35
	s_nop 4
	global_load_dword v8, v0, s[4:5] sc1
	v_readlane_b32 s4, v252, 36
	v_readlane_b32 s5, v252, 37
	s_nop 4
	global_load_dword v9, v0, s[4:5] sc1
	v_readlane_b32 s4, v252, 38
	v_readlane_b32 s5, v252, 39
	s_nop 4
	global_load_dword v10, v0, s[4:5] sc1
	v_readlane_b32 s4, v252, 40
	v_readlane_b32 s5, v252, 41
	s_nop 4
	global_load_dword v11, v0, s[4:5] sc1
	v_readlane_b32 s4, v252, 42
	v_readlane_b32 s5, v252, 43
	s_nop 4
	global_load_dword v12, v0, s[4:5] sc1
	v_readlane_b32 s4, v252, 44
	v_readlane_b32 s5, v252, 45
	s_nop 4
	global_load_dword v13, v0, s[4:5] sc1
	v_readlane_b32 s4, v252, 46
	v_readlane_b32 s5, v252, 47
	s_nop 4
	global_load_dword v14, v0, s[4:5] sc1
	v_readlane_b32 s4, v252, 48
	v_readlane_b32 s5, v252, 49
	s_nop 4
	global_load_dword v15, v0, s[4:5] sc1
	v_readlane_b32 s4, v252, 50
	v_readlane_b32 s5, v252, 51
	s_nop 4
	global_load_dword v16, v0, s[4:5] sc1
	s_mov_b64 s[4:5], -1
	s_waitcnt vmcnt(0)
	v_add_u32_e32 v17, v2, v1
	v_add_u32_e32 v17, v17, v3
	v_add_u32_e32 v17, v17, v4
	v_add_u32_e32 v17, v17, v5
	v_add_u32_e32 v17, v17, v6
	v_add_u32_e32 v17, v17, v7
	v_add_u32_e32 v17, v17, v8
	v_add_u32_e32 v17, v17, v9
	v_add_u32_e32 v17, v17, v10
	v_add_u32_e32 v17, v17, v11
	v_add_u32_e32 v17, v17, v12
	v_add_u32_e32 v17, v17, v13
	v_add_u32_e32 v17, v17, v14
	v_add_u32_e32 v17, v17, v15
	v_add_u32_e32 v17, v17, v16
	v_cmp_eq_u32_e32 vcc, s7, v17
	s_cbranch_vccnz .LBB0_128
	s_and_b32 s4, s6, 0xff
	s_cmp_eq_u32 s4, 0
	s_mov_b64 s[4:5], -1
	s_mov_b64 s[24:25], -1
	s_sleep 1
	s_cbranch_scc0 .LBB0_133
	v_readlane_b32 s4, v252, 18
	v_readlane_b32 s5, v252, 19
	s_nop 4
	global_load_dword v17, v0, s[4:5] sc1
	s_waitcnt vmcnt(0)
	v_cmp_eq_u32_e32 vcc, 0, v17
	s_cbranch_vccnz .LBB0_135
	s_mov_b64 s[24:25], 0
	s_mov_b64 s[4:5], -1
